# expert-table reads in the quantisation loop marked non-temporal (read-once stream should not displace the projection data in the memory-side cache)
# baseline (speedup 1.0000x reference)
.LBB0_360:
	v_add_u32_e32 v87, s73, v75
	v_add_u32_e32 v50, s47, v77
	v_cmp_lt_i32_e32 vcc, s50, v87
	v_and_b32_e32 v50, 0xfffc00, v50
	v_lshlrev_b32_e32 v64, 2, v50
	v_cndmask_b32_e32 v49, v80, v81, vcc
	v_cndmask_b32_e32 v48, v82, v83, vcc
	v_lshl_add_u64 v[48:49], v[48:49], 0, v[64:65]
	v_lshl_add_u64 v[60:61], v[48:49], 0, v[72:73]
	global_load_dwordx4 v[48:51], v[60:61], off offset:48 nt
	global_load_dwordx4 v[52:55], v[60:61], off offset:32 nt
	global_load_dwordx4 v[56:59], v[60:61], off offset:16 nt
	s_nop 0
	global_load_dwordx4 v[60:63], v[60:61], off nt
	v_add_u32_e32 v86, s73, v79
	v_cmp_gt_i32_e64 s[44:45], s49, v87
	v_cmp_gt_i32_e64 s[42:43], s30, v86
	s_and_saveexec_b64 s[0:1], s[42:43]
	s_cbranch_execz .LBB0_362
	v_mov_b32_e32 v24, s89
	v_mov_b32_e32 v25, s91
	v_cmp_lt_i32_e32 vcc, s50, v86
	v_mov_b32_e32 v26, s90
	v_mov_b32_e32 v71, v65
	v_cndmask_b32_e32 v25, v24, v25, vcc
	v_mov_b32_e32 v24, s88
	v_cndmask_b32_e32 v24, v24, v26, vcc
	v_add_u32_e32 v26, s46, v77
	v_and_b32_e32 v26, 0xfffc00, v26
	v_lshlrev_b32_e32 v64, 2, v26
	v_lshl_add_u64 v[24:25], v[24:25], 0, v[64:65]
	v_lshl_add_u64 v[44:45], v[24:25], 0, v[70:71]
	global_load_dwordx4 v[24:27], v[44:45], off offset:48 nt
	global_load_dwordx4 v[32:35], v[44:45], off offset:32 nt
	global_load_dwordx4 v[40:43], v[44:45], off offset:16 nt
	s_nop 0
	global_load_dwordx4 v[44:47], v[44:45], off nt
.LBB0_362:
	s_or_b64 exec, exec, s[0:1]
	v_add_u32_e32 v85, s73, v76
	v_cmp_gt_i32_e64 s[0:1], s30, v85
	s_and_saveexec_b64 s[18:19], s[0:1]
	s_cbranch_execz .LBB0_364
	v_mov_b32_e32 v8, s89
	v_mov_b32_e32 v9, s91
	v_cmp_lt_i32_e32 vcc, s50, v85
	v_mov_b32_e32 v10, s90
	v_mov_b32_e32 v71, v65
	v_cndmask_b32_e32 v9, v8, v9, vcc
	v_mov_b32_e32 v8, s88
	v_cndmask_b32_e32 v8, v8, v10, vcc
	v_add_u32_e32 v10, s33, v77
	v_and_b32_e32 v10, 0xfffc00, v10
	v_lshlrev_b32_e32 v64, 2, v10
	v_lshl_add_u64 v[8:9], v[8:9], 0, v[64:65]
	v_lshl_add_u64 v[36:37], v[8:9], 0, v[70:71]
	global_load_dwordx4 v[8:11], v[36:37], off offset:48 nt
	global_load_dwordx4 v[16:19], v[36:37], off offset:32 nt
	global_load_dwordx4 v[28:31], v[36:37], off offset:16 nt
	s_nop 0
	global_load_dwordx4 v[36:39], v[36:37], off nt
.LBB0_364:
	s_or_b64 exec, exec, s[18:19]
	v_add_u32_e32 v84, s73, v78
	v_cmp_gt_i32_e64 s[40:41], s30, v84
	s_and_saveexec_b64 s[18:19], s[40:41]
	s_cbranch_execz .LBB0_366
	v_mov_b32_e32 v0, s89
	v_mov_b32_e32 v1, s91
	v_cmp_lt_i32_e32 vcc, s50, v84
	v_mov_b32_e32 v2, s90
	v_mov_b32_e32 v71, v65
	v_cndmask_b32_e32 v1, v0, v1, vcc
	v_mov_b32_e32 v0, s88
	v_cndmask_b32_e32 v0, v0, v2, vcc
	v_add_u32_e32 v2, s35, v77
	v_and_b32_e32 v2, 0xfffc00, v2
	v_lshlrev_b32_e32 v64, 2, v2
	v_lshl_add_u64 v[0:1], v[0:1], 0, v[64:65]
	v_lshl_add_u64 v[20:21], v[0:1], 0, v[70:71]
	global_load_dwordx4 v[0:3], v[20:21], off offset:48 nt
	global_load_dwordx4 v[4:7], v[20:21], off offset:32 nt
	global_load_dwordx4 v[12:15], v[20:21], off offset:16 nt
	s_nop 0
	global_load_dwordx4 v[20:23], v[20:21], off nt
